# K-loops: the redundant s_waitcnt lgkmcnt(0) after each segment barrier deleted (16 sites)
# speedup vs baseline: 1.0068x; 1.0068x over previous
.LBB0_178:
	ds_read_b128 v[148:151], v171
	ds_read_b128 v[152:155], v171 offset:1024
	ds_read_b128 v[156:159], v171 offset:2048
	ds_read_b128 v[160:163], v171 offset:3072
	ds_read_b128 v[190:193], v173
	ds_read_b128 v[198:201], v173 offset:1024
	ds_read_b128 v[202:205], v173 offset:2048
	ds_read_b128 v[206:209], v173 offset:3072
	s_add_u32 s54, s52, 0xfffc0080
	s_addc_u32 s55, s53, -1
	s_cmp_eq_u32 s87, 12
	s_cselect_b32 s57, s5, s55
	s_cselect_b32 s56, s10, s54
	s_cselect_b32 s55, s11, s86
	s_cselect_b32 s54, s39, s41
	v_lshl_add_u64 v[166:167], s[52:53], 0, v[140:141]
	s_add_i32 m0, s49, 0xc000
	ds_read_b128 v[210:213], v177
	ds_read_b128 v[214:217], v177 offset:1024
	ds_read_b128 v[218:221], v177 offset:2048
	ds_read_b128 v[222:225], v177 offset:3072
	ds_read_b128 v[226:229], v177 offset:4096
	ds_read_b128 v[230:233], v177 offset:5120
	ds_read_b128 v[234:237], v177 offset:6144
	ds_read_b128 v[238:241], v177 offset:7168
	global_load_lds_dwordx4 v[166:167], off
	v_lshl_add_u64 v[166:167], s[52:53], 0, v[142:143]
	s_add_i32 m0, s49, 0xe000
	s_nop 0
	global_load_lds_dwordx4 v[166:167], off
	s_waitcnt vmcnt(8)
	s_waitcnt lgkmcnt(0)
	s_barrier
	s_setprio 1
	v_mfma_f32_16x16x32_bf16 v[124:127], v[148:151], v[210:213], v[124:127]
	v_mfma_f32_16x16x32_bf16 v[120:123], v[156:159], v[210:213], v[120:123]
	v_mfma_f32_16x16x32_bf16 v[108:111], v[148:151], v[218:221], v[108:111]
	v_mfma_f32_16x16x32_bf16 v[104:107], v[156:159], v[218:221], v[104:107]
	v_mfma_f32_16x16x32_bf16 v[92:95], v[148:151], v[226:229], v[92:95]
	v_mfma_f32_16x16x32_bf16 v[88:91], v[156:159], v[226:229], v[88:91]
	v_mfma_f32_16x16x32_bf16 v[76:79], v[148:151], v[234:237], v[76:79]
	v_mfma_f32_16x16x32_bf16 v[72:75], v[156:159], v[234:237], v[72:75]
	v_mfma_f32_16x16x32_bf16 v[124:127], v[152:155], v[214:217], v[124:127]
	v_mfma_f32_16x16x32_bf16 v[120:123], v[160:163], v[214:217], v[120:123]
	v_mfma_f32_16x16x32_bf16 v[108:111], v[152:155], v[222:225], v[108:111]
	v_mfma_f32_16x16x32_bf16 v[104:107], v[160:163], v[222:225], v[104:107]
	v_mfma_f32_16x16x32_bf16 v[92:95], v[152:155], v[230:233], v[92:95]
	v_mfma_f32_16x16x32_bf16 v[88:91], v[160:163], v[230:233], v[88:91]
	v_mfma_f32_16x16x32_bf16 v[76:79], v[152:155], v[238:241], v[76:79]
	v_mfma_f32_16x16x32_bf16 v[72:75], v[160:163], v[238:241], v[72:75]
	s_setprio 0
	s_setprio 1
	v_mfma_f32_16x16x32_bf16 v[116:119], v[190:193], v[210:213], v[116:119]
	v_mfma_f32_16x16x32_bf16 v[112:115], v[202:205], v[210:213], v[112:115]
	v_mfma_f32_16x16x32_bf16 v[100:103], v[190:193], v[218:221], v[100:103]
	v_mfma_f32_16x16x32_bf16 v[96:99], v[202:205], v[218:221], v[96:99]
	v_mfma_f32_16x16x32_bf16 v[84:87], v[190:193], v[226:229], v[84:87]
	v_mfma_f32_16x16x32_bf16 v[80:83], v[202:205], v[226:229], v[80:83]
	v_mfma_f32_16x16x32_bf16 v[68:71], v[190:193], v[234:237], v[68:71]
	v_mfma_f32_16x16x32_bf16 v[64:67], v[202:205], v[234:237], v[64:67]
	v_mfma_f32_16x16x32_bf16 v[116:119], v[198:201], v[214:217], v[116:119]
	v_mfma_f32_16x16x32_bf16 v[112:115], v[206:209], v[214:217], v[112:115]
	v_mfma_f32_16x16x32_bf16 v[100:103], v[198:201], v[222:225], v[100:103]
	v_mfma_f32_16x16x32_bf16 v[96:99], v[206:209], v[222:225], v[96:99]
	v_mfma_f32_16x16x32_bf16 v[84:87], v[198:201], v[230:233], v[84:87]
	v_mfma_f32_16x16x32_bf16 v[80:83], v[206:209], v[230:233], v[80:83]
	v_mfma_f32_16x16x32_bf16 v[68:71], v[198:201], v[238:241], v[68:71]
	v_mfma_f32_16x16x32_bf16 v[64:67], v[206:209], v[238:241], v[64:67]
	s_setprio 0
	s_barrier
	s_add_i32 s88, s81, s64
	v_lshl_add_u64 v[166:167], s[54:55], 0, v[130:131]
	s_mov_b32 m0, s88
	ds_read_b128 v[210:213], v177 offset:16384
	ds_read_b128 v[214:217], v177 offset:17408
	ds_read_b128 v[218:221], v177 offset:18432
	ds_read_b128 v[222:225], v177 offset:19456
	ds_read_b128 v[226:229], v177 offset:20480
	ds_read_b128 v[230:233], v177 offset:21504
	ds_read_b128 v[234:237], v177 offset:22528
	ds_read_b128 v[238:241], v177 offset:23552
	global_load_lds_dwordx4 v[166:167], off
	s_add_i32 m0, s88, 0x2000
	s_add_u32 s90, s54, 0x40000
	v_lshl_add_u64 v[174:175], s[54:55], 0, v[134:135]
	s_addc_u32 s91, s55, 0
	s_add_i32 s88, s82, s64
	global_load_lds_dwordx4 v[174:175], off
	v_lshl_add_u64 v[178:179], s[90:91], 0, v[130:131]
	s_mov_b32 m0, s88
	v_lshl_add_u64 v[182:183], s[56:57], 0, v[132:133]
	global_load_lds_dwordx4 v[178:179], off
	v_lshl_add_u64 v[178:179], s[90:91], 0, v[134:135]
	s_add_i32 m0, s88, 0x2000
	s_nop 0
	global_load_lds_dwordx4 v[178:179], off
	v_lshl_add_u64 v[178:179], s[56:57], 0, v[128:129]
	s_mov_b32 m0, s49
	s_nop 0
	global_load_lds_dwordx4 v[178:179], off
	s_mov_b32 m0, s65
	s_nop 0
	global_load_lds_dwordx4 v[182:183], off
	s_waitcnt vmcnt(8)
	s_waitcnt lgkmcnt(0)
	s_barrier
	s_setprio 1
	v_mfma_f32_16x16x32_bf16 v[60:63], v[148:151], v[210:213], v[60:63]
	v_mfma_f32_16x16x32_bf16 v[56:59], v[156:159], v[210:213], v[56:59]
	v_mfma_f32_16x16x32_bf16 v[44:47], v[148:151], v[218:221], v[44:47]
	v_mfma_f32_16x16x32_bf16 v[40:43], v[156:159], v[218:221], v[40:43]
	v_mfma_f32_16x16x32_bf16 v[28:31], v[148:151], v[226:229], v[28:31]
	v_mfma_f32_16x16x32_bf16 v[24:27], v[156:159], v[226:229], v[24:27]
	v_mfma_f32_16x16x32_bf16 v[12:15], v[148:151], v[234:237], v[12:15]
	v_mfma_f32_16x16x32_bf16 v[8:11], v[156:159], v[234:237], v[8:11]
	v_mfma_f32_16x16x32_bf16 v[60:63], v[152:155], v[214:217], v[60:63]
	v_mfma_f32_16x16x32_bf16 v[56:59], v[160:163], v[214:217], v[56:59]
	v_mfma_f32_16x16x32_bf16 v[44:47], v[152:155], v[222:225], v[44:47]
	v_mfma_f32_16x16x32_bf16 v[40:43], v[160:163], v[222:225], v[40:43]
	v_mfma_f32_16x16x32_bf16 v[28:31], v[152:155], v[230:233], v[28:31]
	v_mfma_f32_16x16x32_bf16 v[24:27], v[160:163], v[230:233], v[24:27]
	v_mfma_f32_16x16x32_bf16 v[12:15], v[152:155], v[238:241], v[12:15]
	v_mfma_f32_16x16x32_bf16 v[8:11], v[160:163], v[238:241], v[8:11]
	s_setprio 0
	s_setprio 1
	v_mfma_f32_16x16x32_bf16 v[52:55], v[190:193], v[210:213], v[52:55]
	v_mfma_f32_16x16x32_bf16 v[48:51], v[202:205], v[210:213], v[48:51]
	v_mfma_f32_16x16x32_bf16 v[36:39], v[190:193], v[218:221], v[36:39]
	v_mfma_f32_16x16x32_bf16 v[32:35], v[202:205], v[218:221], v[32:35]
	v_mfma_f32_16x16x32_bf16 v[20:23], v[190:193], v[226:229], v[20:23]
	v_mfma_f32_16x16x32_bf16 v[16:19], v[202:205], v[226:229], v[16:19]
	v_mfma_f32_16x16x32_bf16 v[4:7], v[190:193], v[234:237], v[4:7]
	v_mfma_f32_16x16x32_bf16 v[0:3], v[202:205], v[234:237], v[0:3]
	v_mfma_f32_16x16x32_bf16 v[52:55], v[198:201], v[214:217], v[52:55]
	v_mfma_f32_16x16x32_bf16 v[48:51], v[206:209], v[214:217], v[48:51]
	v_mfma_f32_16x16x32_bf16 v[36:39], v[198:201], v[222:225], v[36:39]
	v_mfma_f32_16x16x32_bf16 v[32:35], v[206:209], v[222:225], v[32:35]
	v_mfma_f32_16x16x32_bf16 v[20:23], v[198:201], v[230:233], v[20:23]
	v_mfma_f32_16x16x32_bf16 v[16:19], v[206:209], v[230:233], v[16:19]
	v_mfma_f32_16x16x32_bf16 v[4:7], v[198:201], v[238:241], v[4:7]
	v_mfma_f32_16x16x32_bf16 v[0:3], v[206:209], v[238:241], v[0:3]
	s_setprio 0
	s_barrier
	s_add_i32 s88, 0, 0x18000
	v_add_u32_e32 v136, s88, v169
	s_add_i32 s90, 0, 0x1c000
	ds_read_b128 v[148:151], v136
	ds_read_b128 v[152:155], v136 offset:1024
	ds_read_b128 v[156:159], v136 offset:2048
	ds_read_b128 v[160:163], v136 offset:3072
	v_add_u32_e32 v136, s90, v169
	ds_read_b128 v[190:193], v136
	ds_read_b128 v[198:201], v136 offset:1024
	ds_read_b128 v[202:205], v136 offset:2048
	ds_read_b128 v[206:209], v136 offset:3072
	s_add_u32 s56, s56, 0x40000
	s_addc_u32 s57, s57, 0
	s_mov_b32 m0, s66
	v_lshl_add_u64 v[186:187], s[56:57], 0, v[128:129]
	ds_read_b128 v[210:213], v177 offset:32768
	ds_read_b128 v[214:217], v177 offset:33792
	ds_read_b128 v[218:221], v177 offset:34816
	ds_read_b128 v[222:225], v177 offset:35840
	ds_read_b128 v[226:229], v177 offset:36864
	ds_read_b128 v[230:233], v177 offset:37888
	ds_read_b128 v[234:237], v177 offset:38912
	ds_read_b128 v[238:241], v177 offset:39936
	global_load_lds_dwordx4 v[186:187], off
	v_lshl_add_u64 v[186:187], s[56:57], 0, v[132:133]
	s_mov_b32 m0, s67
	s_nop 0
	global_load_lds_dwordx4 v[186:187], off
	s_waitcnt vmcnt(8)
	s_waitcnt lgkmcnt(0)
	s_barrier
	s_setprio 1
	v_mfma_f32_16x16x32_bf16 v[124:127], v[148:151], v[210:213], v[124:127]
	v_mfma_f32_16x16x32_bf16 v[120:123], v[156:159], v[210:213], v[120:123]
	v_mfma_f32_16x16x32_bf16 v[108:111], v[148:151], v[218:221], v[108:111]
	v_mfma_f32_16x16x32_bf16 v[104:107], v[156:159], v[218:221], v[104:107]
	v_mfma_f32_16x16x32_bf16 v[92:95], v[148:151], v[226:229], v[92:95]
	v_mfma_f32_16x16x32_bf16 v[88:91], v[156:159], v[226:229], v[88:91]
	v_mfma_f32_16x16x32_bf16 v[76:79], v[148:151], v[234:237], v[76:79]
	v_mfma_f32_16x16x32_bf16 v[72:75], v[156:159], v[234:237], v[72:75]
	v_mfma_f32_16x16x32_bf16 v[124:127], v[152:155], v[214:217], v[124:127]
	v_mfma_f32_16x16x32_bf16 v[120:123], v[160:163], v[214:217], v[120:123]
	v_mfma_f32_16x16x32_bf16 v[108:111], v[152:155], v[222:225], v[108:111]
	v_mfma_f32_16x16x32_bf16 v[104:107], v[160:163], v[222:225], v[104:107]
	v_mfma_f32_16x16x32_bf16 v[92:95], v[152:155], v[230:233], v[92:95]
	v_mfma_f32_16x16x32_bf16 v[88:91], v[160:163], v[230:233], v[88:91]
	v_mfma_f32_16x16x32_bf16 v[76:79], v[152:155], v[238:241], v[76:79]
	v_mfma_f32_16x16x32_bf16 v[72:75], v[160:163], v[238:241], v[72:75]
	s_setprio 0
	s_setprio 1
	v_mfma_f32_16x16x32_bf16 v[116:119], v[190:193], v[210:213], v[116:119]
	v_mfma_f32_16x16x32_bf16 v[112:115], v[202:205], v[210:213], v[112:115]
	v_mfma_f32_16x16x32_bf16 v[100:103], v[190:193], v[218:221], v[100:103]
	v_mfma_f32_16x16x32_bf16 v[96:99], v[202:205], v[218:221], v[96:99]
	v_mfma_f32_16x16x32_bf16 v[84:87], v[190:193], v[226:229], v[84:87]
	v_mfma_f32_16x16x32_bf16 v[80:83], v[202:205], v[226:229], v[80:83]
	v_mfma_f32_16x16x32_bf16 v[68:71], v[190:193], v[234:237], v[68:71]
	v_mfma_f32_16x16x32_bf16 v[64:67], v[202:205], v[234:237], v[64:67]
	v_mfma_f32_16x16x32_bf16 v[116:119], v[198:201], v[214:217], v[116:119]
	v_mfma_f32_16x16x32_bf16 v[112:115], v[206:209], v[214:217], v[112:115]
	v_mfma_f32_16x16x32_bf16 v[100:103], v[198:201], v[222:225], v[100:103]
	v_mfma_f32_16x16x32_bf16 v[96:99], v[206:209], v[222:225], v[96:99]
	v_mfma_f32_16x16x32_bf16 v[84:87], v[198:201], v[230:233], v[84:87]
	v_mfma_f32_16x16x32_bf16 v[80:83], v[206:209], v[230:233], v[80:83]
	v_mfma_f32_16x16x32_bf16 v[68:71], v[198:201], v[238:241], v[68:71]
	v_mfma_f32_16x16x32_bf16 v[64:67], v[206:209], v[238:241], v[64:67]
	s_setprio 0
	s_barrier
	s_add_i32 s56, s88, s64
	v_lshl_add_u64 v[166:167], v[166:167], 0, s[14:15]
	s_mov_b32 m0, s56
	ds_read_b128 v[210:213], v177 offset:49152
	ds_read_b128 v[214:217], v177 offset:50176
	ds_read_b128 v[218:221], v177 offset:51200
	ds_read_b128 v[222:225], v177 offset:52224
	ds_read_b128 v[226:229], v177 offset:53248
	ds_read_b128 v[230:233], v177 offset:54272
	ds_read_b128 v[234:237], v177 offset:55296
	ds_read_b128 v[238:241], v177 offset:56320
	global_load_lds_dwordx4 v[166:167], off
	s_add_i32 m0, s56, 0x2000
	s_add_u32 s54, s54, 0x40080
	v_lshl_add_u64 v[166:167], v[174:175], 0, s[14:15]
	s_addc_u32 s55, s55, 0
	s_add_i32 s56, s90, s64
	global_load_lds_dwordx4 v[166:167], off
	v_lshl_add_u64 v[166:167], s[54:55], 0, v[130:131]
	s_mov_b32 m0, s56
	s_nop 0
	global_load_lds_dwordx4 v[166:167], off
	v_lshl_add_u64 v[166:167], s[54:55], 0, v[134:135]
	s_add_i32 m0, s56, 0x2000
	s_nop 0
	global_load_lds_dwordx4 v[166:167], off
	v_lshl_add_u64 v[166:167], v[178:179], 0, s[14:15]
	s_mov_b32 m0, s76
	s_nop 0
	global_load_lds_dwordx4 v[166:167], off
	v_lshl_add_u64 v[166:167], v[182:183], 0, s[14:15]
	s_mov_b32 m0, s77
	s_nop 0
	global_load_lds_dwordx4 v[166:167], off
	s_waitcnt vmcnt(8)
	s_waitcnt lgkmcnt(0)
	s_barrier
	s_setprio 1
	v_mfma_f32_16x16x32_bf16 v[60:63], v[148:151], v[210:213], v[60:63]
	v_mfma_f32_16x16x32_bf16 v[56:59], v[156:159], v[210:213], v[56:59]
	v_mfma_f32_16x16x32_bf16 v[44:47], v[148:151], v[218:221], v[44:47]
	v_mfma_f32_16x16x32_bf16 v[40:43], v[156:159], v[218:221], v[40:43]
	v_mfma_f32_16x16x32_bf16 v[28:31], v[148:151], v[226:229], v[28:31]
	v_mfma_f32_16x16x32_bf16 v[24:27], v[156:159], v[226:229], v[24:27]
	v_mfma_f32_16x16x32_bf16 v[12:15], v[148:151], v[234:237], v[12:15]
	v_mfma_f32_16x16x32_bf16 v[8:11], v[156:159], v[234:237], v[8:11]
	v_mfma_f32_16x16x32_bf16 v[60:63], v[152:155], v[214:217], v[60:63]
	v_mfma_f32_16x16x32_bf16 v[56:59], v[160:163], v[214:217], v[56:59]
	v_mfma_f32_16x16x32_bf16 v[44:47], v[152:155], v[222:225], v[44:47]
	v_mfma_f32_16x16x32_bf16 v[40:43], v[160:163], v[222:225], v[40:43]
	v_mfma_f32_16x16x32_bf16 v[28:31], v[152:155], v[230:233], v[28:31]
	v_mfma_f32_16x16x32_bf16 v[24:27], v[160:163], v[230:233], v[24:27]
	v_mfma_f32_16x16x32_bf16 v[12:15], v[152:155], v[238:241], v[12:15]
	v_mfma_f32_16x16x32_bf16 v[8:11], v[160:163], v[238:241], v[8:11]
	s_setprio 0
	s_setprio 1
	v_mfma_f32_16x16x32_bf16 v[52:55], v[190:193], v[210:213], v[52:55]
	v_mfma_f32_16x16x32_bf16 v[48:51], v[202:205], v[210:213], v[48:51]
	v_mfma_f32_16x16x32_bf16 v[36:39], v[190:193], v[218:221], v[36:39]
	v_mfma_f32_16x16x32_bf16 v[32:35], v[202:205], v[218:221], v[32:35]
	v_mfma_f32_16x16x32_bf16 v[20:23], v[190:193], v[226:229], v[20:23]
	v_mfma_f32_16x16x32_bf16 v[16:19], v[202:205], v[226:229], v[16:19]
	v_mfma_f32_16x16x32_bf16 v[4:7], v[190:193], v[234:237], v[4:7]
	v_mfma_f32_16x16x32_bf16 v[0:3], v[202:205], v[234:237], v[0:3]
	v_mfma_f32_16x16x32_bf16 v[52:55], v[198:201], v[214:217], v[52:55]
	v_mfma_f32_16x16x32_bf16 v[48:51], v[206:209], v[214:217], v[48:51]
	v_mfma_f32_16x16x32_bf16 v[36:39], v[198:201], v[222:225], v[36:39]
	v_mfma_f32_16x16x32_bf16 v[32:35], v[206:209], v[222:225], v[32:35]
	v_mfma_f32_16x16x32_bf16 v[20:23], v[198:201], v[230:233], v[20:23]
	v_mfma_f32_16x16x32_bf16 v[16:19], v[206:209], v[230:233], v[16:19]
	v_mfma_f32_16x16x32_bf16 v[4:7], v[198:201], v[238:241], v[4:7]
	v_mfma_f32_16x16x32_bf16 v[0:3], v[206:209], v[238:241], v[0:3]
	s_setprio 0
	s_barrier
	s_add_i32 s87, s87, 2
	s_add_u32 s52, s52, 0x100
	s_addc_u32 s53, s53, 0
	s_add_u32 s41, s41, 0x100
	s_addc_u32 s86, s86, 0
	s_cmp_gt_u32 s87, 13
	s_cbranch_scc0 .LBB0_178
	s_and_b64 vcc, exec, s[16:17]
	s_cbranch_vccz .LBB0_181
	s_barrier

.LBB0_492:
	ds_read_b128 v[96:99], v222
	ds_read_b128 v[108:111], v222 offset:1024
	ds_read_b128 v[120:123], v222 offset:2048
	ds_read_b128 v[128:131], v222 offset:3072
	ds_read_b128 v[144:147], v223
	ds_read_b128 v[148:151], v223 offset:1024
	ds_read_b128 v[152:155], v223 offset:2048
	ds_read_b128 v[156:159], v223 offset:3072
	s_add_u32 s46, s44, 0xfffc0080
	s_addc_u32 s47, s45, -1
	s_cmp_eq_u32 s72, 12
	s_cselect_b32 s49, s10, s47
	s_cselect_b32 s48, s11, s46
	s_cselect_b32 s47, s35, s67
	s_cselect_b32 s46, s37, s43
	v_lshl_add_u64 v[210:211], s[44:45], 0, v[192:193]
	s_add_i32 m0, s54, 0xc000
	ds_read_b128 v[160:163], v224
	ds_read_b128 v[164:167], v224 offset:1024
	ds_read_b128 v[168:171], v224 offset:2048
	ds_read_b128 v[172:175], v224 offset:3072
	ds_read_b128 v[176:179], v224 offset:4096
	ds_read_b128 v[180:183], v224 offset:5120
	ds_read_b128 v[202:205], v224 offset:6144
	ds_read_b128 v[206:209], v224 offset:7168
	global_load_lds_dwordx4 v[210:211], off
	v_lshl_add_u64 v[210:211], s[44:45], 0, v[194:195]
	s_add_i32 m0, s54, 0xe000
	s_nop 0
	global_load_lds_dwordx4 v[210:211], off
	s_waitcnt vmcnt(8)
	s_waitcnt lgkmcnt(0)
	s_barrier
	s_setprio 1
	v_mfma_f32_16x16x32_bf16 v[140:143], v[96:99], v[160:163], v[140:143]
	v_mfma_f32_16x16x32_bf16 v[136:139], v[120:123], v[160:163], v[136:139]
	v_mfma_f32_16x16x32_bf16 v[116:119], v[96:99], v[168:171], v[116:119]
	v_mfma_f32_16x16x32_bf16 v[112:115], v[120:123], v[168:171], v[112:115]
	v_mfma_f32_16x16x32_bf16 v[92:95], v[96:99], v[176:179], v[92:95]
	v_mfma_f32_16x16x32_bf16 v[88:91], v[120:123], v[176:179], v[88:91]
	v_mfma_f32_16x16x32_bf16 v[76:79], v[96:99], v[202:205], v[76:79]
	v_mfma_f32_16x16x32_bf16 v[72:75], v[120:123], v[202:205], v[72:75]
	v_mfma_f32_16x16x32_bf16 v[140:143], v[108:111], v[164:167], v[140:143]
	v_mfma_f32_16x16x32_bf16 v[136:139], v[128:131], v[164:167], v[136:139]
	v_mfma_f32_16x16x32_bf16 v[116:119], v[108:111], v[172:175], v[116:119]
	v_mfma_f32_16x16x32_bf16 v[112:115], v[128:131], v[172:175], v[112:115]
	v_mfma_f32_16x16x32_bf16 v[92:95], v[108:111], v[180:183], v[92:95]
	v_mfma_f32_16x16x32_bf16 v[88:91], v[128:131], v[180:183], v[88:91]
	v_mfma_f32_16x16x32_bf16 v[76:79], v[108:111], v[206:209], v[76:79]
	v_mfma_f32_16x16x32_bf16 v[72:75], v[128:131], v[206:209], v[72:75]
	s_setprio 0
	s_setprio 1
	v_mfma_f32_16x16x32_bf16 v[132:135], v[144:147], v[160:163], v[132:135]
	v_mfma_f32_16x16x32_bf16 v[124:127], v[152:155], v[160:163], v[124:127]
	v_mfma_f32_16x16x32_bf16 v[104:107], v[144:147], v[168:171], v[104:107]
	v_mfma_f32_16x16x32_bf16 v[100:103], v[152:155], v[168:171], v[100:103]
	v_mfma_f32_16x16x32_bf16 v[84:87], v[144:147], v[176:179], v[84:87]
	v_mfma_f32_16x16x32_bf16 v[80:83], v[152:155], v[176:179], v[80:83]
	v_mfma_f32_16x16x32_bf16 v[68:71], v[144:147], v[202:205], v[68:71]
	v_mfma_f32_16x16x32_bf16 v[64:67], v[152:155], v[202:205], v[64:67]
	v_mfma_f32_16x16x32_bf16 v[132:135], v[148:151], v[164:167], v[132:135]
	v_mfma_f32_16x16x32_bf16 v[124:127], v[156:159], v[164:167], v[124:127]
	v_mfma_f32_16x16x32_bf16 v[104:107], v[148:151], v[172:175], v[104:107]
	v_mfma_f32_16x16x32_bf16 v[100:103], v[156:159], v[172:175], v[100:103]
	v_mfma_f32_16x16x32_bf16 v[84:87], v[148:151], v[180:183], v[84:87]
	v_mfma_f32_16x16x32_bf16 v[80:83], v[156:159], v[180:183], v[80:83]
	v_mfma_f32_16x16x32_bf16 v[68:71], v[148:151], v[206:209], v[68:71]
	v_mfma_f32_16x16x32_bf16 v[64:67], v[156:159], v[206:209], v[64:67]
	s_setprio 0
	s_barrier
	s_add_i32 s73, s64, s53
	v_lshl_add_u64 v[210:211], s[46:47], 0, v[186:187]
	s_mov_b32 m0, s73
	ds_read_b128 v[160:163], v224 offset:16384
	ds_read_b128 v[164:167], v224 offset:17408
	ds_read_b128 v[168:171], v224 offset:18432
	ds_read_b128 v[172:175], v224 offset:19456
	ds_read_b128 v[176:179], v224 offset:20480
	ds_read_b128 v[180:183], v224 offset:21504
	ds_read_b128 v[202:205], v224 offset:22528
	ds_read_b128 v[206:209], v224 offset:23552
	global_load_lds_dwordx4 v[210:211], off
	s_add_i32 m0, s73, 0x2000
	s_add_u32 s74, s46, 0x40000
	v_lshl_add_u64 v[212:213], s[46:47], 0, v[190:191]
	s_addc_u32 s75, s47, 0
	s_add_i32 s73, s65, s53
	global_load_lds_dwordx4 v[212:213], off
	v_lshl_add_u64 v[214:215], s[74:75], 0, v[186:187]
	s_mov_b32 m0, s73
	v_lshl_add_u64 v[216:217], s[48:49], 0, v[188:189]
	global_load_lds_dwordx4 v[214:215], off
	v_lshl_add_u64 v[214:215], s[74:75], 0, v[190:191]
	s_add_i32 m0, s73, 0x2000
	s_nop 0
	global_load_lds_dwordx4 v[214:215], off
	v_lshl_add_u64 v[214:215], s[48:49], 0, v[184:185]
	s_mov_b32 m0, s54
	s_nop 0
	global_load_lds_dwordx4 v[214:215], off
	s_mov_b32 m0, s55
	s_nop 0
	global_load_lds_dwordx4 v[216:217], off
	s_waitcnt vmcnt(8)
	s_waitcnt lgkmcnt(0)
	s_barrier
	s_setprio 1
	v_mfma_f32_16x16x32_bf16 v[60:63], v[96:99], v[160:163], v[60:63]
	v_mfma_f32_16x16x32_bf16 v[56:59], v[120:123], v[160:163], v[56:59]
	v_mfma_f32_16x16x32_bf16 v[44:47], v[96:99], v[168:171], v[44:47]
	v_mfma_f32_16x16x32_bf16 v[40:43], v[120:123], v[168:171], v[40:43]
	v_mfma_f32_16x16x32_bf16 v[28:31], v[96:99], v[176:179], v[28:31]
	v_mfma_f32_16x16x32_bf16 v[24:27], v[120:123], v[176:179], v[24:27]
	v_mfma_f32_16x16x32_bf16 v[12:15], v[96:99], v[202:205], v[12:15]
	v_mfma_f32_16x16x32_bf16 v[8:11], v[120:123], v[202:205], v[8:11]
	v_mfma_f32_16x16x32_bf16 v[60:63], v[108:111], v[164:167], v[60:63]
	v_mfma_f32_16x16x32_bf16 v[56:59], v[128:131], v[164:167], v[56:59]
	v_mfma_f32_16x16x32_bf16 v[44:47], v[108:111], v[172:175], v[44:47]
	v_mfma_f32_16x16x32_bf16 v[40:43], v[128:131], v[172:175], v[40:43]
	v_mfma_f32_16x16x32_bf16 v[28:31], v[108:111], v[180:183], v[28:31]
	v_mfma_f32_16x16x32_bf16 v[24:27], v[128:131], v[180:183], v[24:27]
	v_mfma_f32_16x16x32_bf16 v[12:15], v[108:111], v[206:209], v[12:15]
	v_mfma_f32_16x16x32_bf16 v[8:11], v[128:131], v[206:209], v[8:11]
	s_setprio 0
	s_setprio 1
	v_mfma_f32_16x16x32_bf16 v[52:55], v[144:147], v[160:163], v[52:55]
	v_mfma_f32_16x16x32_bf16 v[48:51], v[152:155], v[160:163], v[48:51]
	v_mfma_f32_16x16x32_bf16 v[36:39], v[144:147], v[168:171], v[36:39]
	v_mfma_f32_16x16x32_bf16 v[32:35], v[152:155], v[168:171], v[32:35]
	v_mfma_f32_16x16x32_bf16 v[20:23], v[144:147], v[176:179], v[20:23]
	v_mfma_f32_16x16x32_bf16 v[16:19], v[152:155], v[176:179], v[16:19]
	v_mfma_f32_16x16x32_bf16 v[4:7], v[144:147], v[202:205], v[4:7]
	v_mfma_f32_16x16x32_bf16 v[0:3], v[152:155], v[202:205], v[0:3]
	v_mfma_f32_16x16x32_bf16 v[52:55], v[148:151], v[164:167], v[52:55]
	v_mfma_f32_16x16x32_bf16 v[48:51], v[156:159], v[164:167], v[48:51]
	v_mfma_f32_16x16x32_bf16 v[36:39], v[148:151], v[172:175], v[36:39]
	v_mfma_f32_16x16x32_bf16 v[32:35], v[156:159], v[172:175], v[32:35]
	v_mfma_f32_16x16x32_bf16 v[20:23], v[148:151], v[180:183], v[20:23]
	v_mfma_f32_16x16x32_bf16 v[16:19], v[156:159], v[180:183], v[16:19]
	v_mfma_f32_16x16x32_bf16 v[4:7], v[148:151], v[206:209], v[4:7]
	v_mfma_f32_16x16x32_bf16 v[0:3], v[156:159], v[206:209], v[0:3]
	s_setprio 0
	s_barrier
	s_add_i32 s73, 0, 0x18000
	s_add_i32 s74, 0, 0x1c000
	v_add_u32_e32 v128, s73, v220
	v_add_u32_e32 v156, s74, v220
	ds_read_b128 v[96:99], v128
	ds_read_b128 v[108:111], v128 offset:1024
	ds_read_b128 v[120:123], v128 offset:2048
	ds_read_b128 v[128:131], v128 offset:3072
	ds_read_b128 v[144:147], v156
	ds_read_b128 v[148:151], v156 offset:1024
	ds_read_b128 v[152:155], v156 offset:2048
	ds_read_b128 v[156:159], v156 offset:3072
	s_add_u32 s48, s48, 0x40000
	s_addc_u32 s49, s49, 0
	s_mov_b32 m0, s56
	v_lshl_add_u64 v[218:219], s[48:49], 0, v[184:185]
	ds_read_b128 v[160:163], v224 offset:32768
	ds_read_b128 v[164:167], v224 offset:33792
	ds_read_b128 v[168:171], v224 offset:34816
	ds_read_b128 v[172:175], v224 offset:35840
	ds_read_b128 v[176:179], v224 offset:36864
	ds_read_b128 v[180:183], v224 offset:37888
	ds_read_b128 v[202:205], v224 offset:38912
	ds_read_b128 v[206:209], v224 offset:39936
	global_load_lds_dwordx4 v[218:219], off
	v_lshl_add_u64 v[218:219], s[48:49], 0, v[188:189]
	s_mov_b32 m0, s57
	s_nop 0
	global_load_lds_dwordx4 v[218:219], off
	s_waitcnt vmcnt(8)
	s_waitcnt lgkmcnt(0)
	s_barrier
	s_setprio 1
	v_mfma_f32_16x16x32_bf16 v[140:143], v[96:99], v[160:163], v[140:143]
	v_mfma_f32_16x16x32_bf16 v[136:139], v[120:123], v[160:163], v[136:139]
	v_mfma_f32_16x16x32_bf16 v[116:119], v[96:99], v[168:171], v[116:119]
	v_mfma_f32_16x16x32_bf16 v[112:115], v[120:123], v[168:171], v[112:115]
	v_mfma_f32_16x16x32_bf16 v[92:95], v[96:99], v[176:179], v[92:95]
	v_mfma_f32_16x16x32_bf16 v[88:91], v[120:123], v[176:179], v[88:91]
	v_mfma_f32_16x16x32_bf16 v[76:79], v[96:99], v[202:205], v[76:79]
	v_mfma_f32_16x16x32_bf16 v[72:75], v[120:123], v[202:205], v[72:75]
	v_mfma_f32_16x16x32_bf16 v[140:143], v[108:111], v[164:167], v[140:143]
	v_mfma_f32_16x16x32_bf16 v[136:139], v[128:131], v[164:167], v[136:139]
	v_mfma_f32_16x16x32_bf16 v[116:119], v[108:111], v[172:175], v[116:119]
	v_mfma_f32_16x16x32_bf16 v[112:115], v[128:131], v[172:175], v[112:115]
	v_mfma_f32_16x16x32_bf16 v[92:95], v[108:111], v[180:183], v[92:95]
	v_mfma_f32_16x16x32_bf16 v[88:91], v[128:131], v[180:183], v[88:91]
	v_mfma_f32_16x16x32_bf16 v[76:79], v[108:111], v[206:209], v[76:79]
	v_mfma_f32_16x16x32_bf16 v[72:75], v[128:131], v[206:209], v[72:75]
	s_setprio 0
	s_setprio 1
	v_mfma_f32_16x16x32_bf16 v[132:135], v[144:147], v[160:163], v[132:135]
	v_mfma_f32_16x16x32_bf16 v[124:127], v[152:155], v[160:163], v[124:127]
	v_mfma_f32_16x16x32_bf16 v[104:107], v[144:147], v[168:171], v[104:107]
	v_mfma_f32_16x16x32_bf16 v[100:103], v[152:155], v[168:171], v[100:103]
	v_mfma_f32_16x16x32_bf16 v[84:87], v[144:147], v[176:179], v[84:87]
	v_mfma_f32_16x16x32_bf16 v[80:83], v[152:155], v[176:179], v[80:83]
	v_mfma_f32_16x16x32_bf16 v[68:71], v[144:147], v[202:205], v[68:71]
	v_mfma_f32_16x16x32_bf16 v[64:67], v[152:155], v[202:205], v[64:67]
	v_mfma_f32_16x16x32_bf16 v[132:135], v[148:151], v[164:167], v[132:135]
	v_mfma_f32_16x16x32_bf16 v[124:127], v[156:159], v[164:167], v[124:127]
	v_mfma_f32_16x16x32_bf16 v[104:107], v[148:151], v[172:175], v[104:107]
	v_mfma_f32_16x16x32_bf16 v[100:103], v[156:159], v[172:175], v[100:103]
	v_mfma_f32_16x16x32_bf16 v[84:87], v[148:151], v[180:183], v[84:87]
	v_mfma_f32_16x16x32_bf16 v[80:83], v[156:159], v[180:183], v[80:83]
	v_mfma_f32_16x16x32_bf16 v[68:71], v[148:151], v[206:209], v[68:71]
	v_mfma_f32_16x16x32_bf16 v[64:67], v[156:159], v[206:209], v[64:67]
	s_setprio 0
	s_barrier
	s_add_i32 s48, s73, s53
	v_lshl_add_u64 v[210:211], v[210:211], 0, s[20:21]
	s_mov_b32 m0, s48
	ds_read_b128 v[160:163], v224 offset:49152
	ds_read_b128 v[164:167], v224 offset:50176
	ds_read_b128 v[168:171], v224 offset:51200
	ds_read_b128 v[172:175], v224 offset:52224
	ds_read_b128 v[176:179], v224 offset:53248
	ds_read_b128 v[180:183], v224 offset:54272
	ds_read_b128 v[202:205], v224 offset:55296
	ds_read_b128 v[206:209], v224 offset:56320
	global_load_lds_dwordx4 v[210:211], off
	s_add_i32 m0, s48, 0x2000
	s_add_u32 s46, s46, 0x40080
	v_lshl_add_u64 v[210:211], v[212:213], 0, s[20:21]
	s_addc_u32 s47, s47, 0
	s_add_i32 s48, s74, s53
	global_load_lds_dwordx4 v[210:211], off
	v_lshl_add_u64 v[210:211], s[46:47], 0, v[186:187]
	s_mov_b32 m0, s48
	s_nop 0
	global_load_lds_dwordx4 v[210:211], off
	v_lshl_add_u64 v[210:211], s[46:47], 0, v[190:191]
	s_add_i32 m0, s48, 0x2000
	s_nop 0
	global_load_lds_dwordx4 v[210:211], off
	v_lshl_add_u64 v[210:211], v[214:215], 0, s[20:21]
	s_mov_b32 m0, s59
	s_nop 0
	global_load_lds_dwordx4 v[210:211], off
	v_lshl_add_u64 v[210:211], v[216:217], 0, s[20:21]
	s_mov_b32 m0, s60
	s_nop 0
	global_load_lds_dwordx4 v[210:211], off
	s_waitcnt vmcnt(8)
	s_waitcnt lgkmcnt(0)
	s_barrier
	s_setprio 1
	v_mfma_f32_16x16x32_bf16 v[60:63], v[96:99], v[160:163], v[60:63]
	v_mfma_f32_16x16x32_bf16 v[56:59], v[120:123], v[160:163], v[56:59]
	v_mfma_f32_16x16x32_bf16 v[44:47], v[96:99], v[168:171], v[44:47]
	v_mfma_f32_16x16x32_bf16 v[40:43], v[120:123], v[168:171], v[40:43]
	v_mfma_f32_16x16x32_bf16 v[28:31], v[96:99], v[176:179], v[28:31]
	v_mfma_f32_16x16x32_bf16 v[24:27], v[120:123], v[176:179], v[24:27]
	v_mfma_f32_16x16x32_bf16 v[12:15], v[96:99], v[202:205], v[12:15]
	v_mfma_f32_16x16x32_bf16 v[8:11], v[120:123], v[202:205], v[8:11]
	v_mfma_f32_16x16x32_bf16 v[60:63], v[108:111], v[164:167], v[60:63]
	v_mfma_f32_16x16x32_bf16 v[56:59], v[128:131], v[164:167], v[56:59]
	v_mfma_f32_16x16x32_bf16 v[44:47], v[108:111], v[172:175], v[44:47]
	v_mfma_f32_16x16x32_bf16 v[40:43], v[128:131], v[172:175], v[40:43]
	v_mfma_f32_16x16x32_bf16 v[28:31], v[108:111], v[180:183], v[28:31]
	v_mfma_f32_16x16x32_bf16 v[24:27], v[128:131], v[180:183], v[24:27]
	v_mfma_f32_16x16x32_bf16 v[12:15], v[108:111], v[206:209], v[12:15]
	v_mfma_f32_16x16x32_bf16 v[8:11], v[128:131], v[206:209], v[8:11]
	s_setprio 0
	s_setprio 1
	v_mfma_f32_16x16x32_bf16 v[52:55], v[144:147], v[160:163], v[52:55]
	v_mfma_f32_16x16x32_bf16 v[48:51], v[152:155], v[160:163], v[48:51]
	v_mfma_f32_16x16x32_bf16 v[36:39], v[144:147], v[168:171], v[36:39]
	v_mfma_f32_16x16x32_bf16 v[32:35], v[152:155], v[168:171], v[32:35]
	v_mfma_f32_16x16x32_bf16 v[20:23], v[144:147], v[176:179], v[20:23]
	v_mfma_f32_16x16x32_bf16 v[16:19], v[152:155], v[176:179], v[16:19]
	v_mfma_f32_16x16x32_bf16 v[4:7], v[144:147], v[202:205], v[4:7]
	v_mfma_f32_16x16x32_bf16 v[0:3], v[152:155], v[202:205], v[0:3]
	v_mfma_f32_16x16x32_bf16 v[52:55], v[148:151], v[164:167], v[52:55]
	v_mfma_f32_16x16x32_bf16 v[48:51], v[156:159], v[164:167], v[48:51]
	v_mfma_f32_16x16x32_bf16 v[36:39], v[148:151], v[172:175], v[36:39]
	v_mfma_f32_16x16x32_bf16 v[32:35], v[156:159], v[172:175], v[32:35]
	v_mfma_f32_16x16x32_bf16 v[20:23], v[148:151], v[180:183], v[20:23]
	v_mfma_f32_16x16x32_bf16 v[16:19], v[156:159], v[180:183], v[16:19]
	v_mfma_f32_16x16x32_bf16 v[4:7], v[148:151], v[206:209], v[4:7]
	v_mfma_f32_16x16x32_bf16 v[0:3], v[156:159], v[206:209], v[0:3]
	s_setprio 0
	s_barrier
	s_add_i32 s72, s72, 2
	s_add_u32 s44, s44, 0x100
	s_addc_u32 s45, s45, 0
	s_add_u32 s43, s43, 0x100
	s_addc_u32 s67, s67, 0
	s_cmp_gt_u32 s72, 13
	s_cbranch_scc0 .LBB0_492
	s_and_b64 vcc, exec, s[26:27]
	s_cbranch_vccz .LBB0_495
	s_barrier

.LBB0_577:
	ds_read_b128 v[108:111], v245
	ds_read_b128 v[116:119], v245 offset:1024
	ds_read_b128 v[120:123], v245 offset:2048
	ds_read_b128 v[124:127], v245 offset:3072
	ds_read_b128 v[128:131], v246
	ds_read_b128 v[132:135], v246 offset:1024
	ds_read_b128 v[136:139], v246 offset:2048
	ds_read_b128 v[140:143], v246 offset:3072
	s_add_u32 s62, s8, 0xfffc0080
	s_addc_u32 s63, s9, -1
	s_cmp_eq_u32 s86, 12
	s_cselect_b32 s65, s10, s63
	s_cselect_b32 s64, s11, s62
	s_cselect_b32 s63, s51, s61
	s_cselect_b32 s62, s53, s59
	v_lshl_add_u64 v[220:221], s[8:9], 0, v[212:213]
	s_add_i32 m0, s74, 0xc000
	ds_read_b128 v[144:147], v247
	ds_read_b128 v[148:151], v247 offset:1024
	ds_read_b128 v[168:171], v247 offset:2048
	ds_read_b128 v[172:175], v247 offset:3072
	ds_read_b128 v[176:179], v247 offset:4096
	ds_read_b128 v[180:183], v247 offset:5120
	ds_read_b128 v[184:187], v247 offset:6144
	ds_read_b128 v[188:191], v247 offset:7168
	global_load_lds_dwordx4 v[220:221], off
	v_lshl_add_u64 v[220:221], s[8:9], 0, v[214:215]
	s_add_i32 m0, s74, 0xe000
	s_nop 0
	global_load_lds_dwordx4 v[220:221], off
	s_waitcnt vmcnt(8)
	s_waitcnt lgkmcnt(0)
	s_barrier
	s_setprio 1
	v_mfma_f32_16x16x32_bf16 v[52:55], v[108:111], v[144:147], v[52:55]
	v_mfma_f32_16x16x32_bf16 v[44:47], v[120:123], v[144:147], v[44:47]
	v_mfma_f32_16x16x32_bf16 v[164:167], v[108:111], v[168:171], v[164:167]
	v_mfma_f32_16x16x32_bf16 v[68:71], v[120:123], v[168:171], v[68:71]
	v_mfma_f32_16x16x32_bf16 v[160:163], v[108:111], v[176:179], v[160:163]
	v_mfma_f32_16x16x32_bf16 v[60:63], v[120:123], v[176:179], v[60:63]
	v_mfma_f32_16x16x32_bf16 v[84:87], v[108:111], v[184:187], v[84:87]
	v_mfma_f32_16x16x32_bf16 v[80:83], v[120:123], v[184:187], v[80:83]
	v_mfma_f32_16x16x32_bf16 v[52:55], v[116:119], v[148:151], v[52:55]
	v_mfma_f32_16x16x32_bf16 v[44:47], v[124:127], v[148:151], v[44:47]
	v_mfma_f32_16x16x32_bf16 v[164:167], v[116:119], v[172:175], v[164:167]
	v_mfma_f32_16x16x32_bf16 v[68:71], v[124:127], v[172:175], v[68:71]
	v_mfma_f32_16x16x32_bf16 v[160:163], v[116:119], v[180:183], v[160:163]
	v_mfma_f32_16x16x32_bf16 v[60:63], v[124:127], v[180:183], v[60:63]
	v_mfma_f32_16x16x32_bf16 v[84:87], v[116:119], v[188:191], v[84:87]
	v_mfma_f32_16x16x32_bf16 v[80:83], v[124:127], v[188:191], v[80:83]
	s_setprio 0
	s_setprio 1
	v_mfma_f32_16x16x32_bf16 v[36:39], v[128:131], v[144:147], v[36:39]
	v_mfma_f32_16x16x32_bf16 v[28:31], v[136:139], v[144:147], v[28:31]
	v_mfma_f32_16x16x32_bf16 v[64:67], v[136:139], v[168:171], v[64:67]
	v_mfma_f32_16x16x32_bf16 v[56:59], v[136:139], v[176:179], v[56:59]
	v_mfma_f32_16x16x32_bf16 v[76:79], v[128:131], v[184:187], v[76:79]
	v_mfma_f32_16x16x32_bf16 v[72:75], v[136:139], v[184:187], v[72:75]
	v_mfma_f32_16x16x32_bf16 v[36:39], v[132:135], v[148:151], v[36:39]
	v_mfma_f32_16x16x32_bf16 v[28:31], v[140:143], v[148:151], v[28:31]
	v_mfma_f32_16x16x32_bf16 v[144:147], v[128:131], v[168:171], v[152:155]
	v_mfma_f32_16x16x32_bf16 v[64:67], v[140:143], v[172:175], v[64:67]
	v_mfma_f32_16x16x32_bf16 v[148:151], v[128:131], v[176:179], v[156:159]
	v_mfma_f32_16x16x32_bf16 v[56:59], v[140:143], v[180:183], v[56:59]
	v_mfma_f32_16x16x32_bf16 v[76:79], v[132:135], v[188:191], v[76:79]
	v_mfma_f32_16x16x32_bf16 v[72:75], v[140:143], v[188:191], v[72:75]
	v_mfma_f32_16x16x32_bf16 v[144:147], v[132:135], v[172:175], v[144:147]
	v_mfma_f32_16x16x32_bf16 v[148:151], v[132:135], v[180:183], v[148:151]
	s_setprio 0
	s_barrier
	s_add_i32 s87, s89, s73
	v_lshl_add_u64 v[220:221], s[62:63], 0, v[194:195]
	s_mov_b32 m0, s87
	ds_read_b128 v[152:155], v247 offset:16384
	ds_read_b128 v[156:159], v247 offset:17408
	ds_read_b128 v[168:171], v247 offset:18432
	ds_read_b128 v[172:175], v247 offset:19456
	ds_read_b128 v[176:179], v247 offset:20480
	ds_read_b128 v[180:183], v247 offset:21504
	ds_read_b128 v[184:187], v247 offset:22528
	ds_read_b128 v[188:191], v247 offset:23552
	global_load_lds_dwordx4 v[220:221], off
	s_add_i32 m0, s87, 0x2000
	s_add_u32 s96, s62, 0x40000
	v_lshl_add_u64 v[222:223], s[62:63], 0, v[200:201]
	s_addc_u32 s97, s63, 0
	s_add_i32 s87, s90, s73
	global_load_lds_dwordx4 v[222:223], off
	v_lshl_add_u64 v[224:225], s[96:97], 0, v[194:195]
	s_mov_b32 m0, s87
	v_lshl_add_u64 v[226:227], s[64:65], 0, v[198:199]
	global_load_lds_dwordx4 v[224:225], off
	v_lshl_add_u64 v[224:225], s[96:97], 0, v[200:201]
	s_add_i32 m0, s87, 0x2000
	s_nop 0
	global_load_lds_dwordx4 v[224:225], off
	v_lshl_add_u64 v[224:225], s[64:65], 0, v[192:193]
	s_mov_b32 m0, s74
	s_nop 0
	global_load_lds_dwordx4 v[224:225], off
	s_mov_b32 m0, s75
	s_nop 0
	global_load_lds_dwordx4 v[226:227], off
	s_waitcnt vmcnt(8)
	s_waitcnt lgkmcnt(0)
	s_barrier
	s_setprio 1
	v_mfma_f32_16x16x32_bf16 v[112:115], v[108:111], v[152:155], v[112:115]
	v_mfma_f32_16x16x32_bf16 v[20:23], v[120:123], v[152:155], v[20:23]
	v_mfma_f32_16x16x32_bf16 v[104:107], v[108:111], v[168:171], v[104:107]
	v_mfma_f32_16x16x32_bf16 v[16:19], v[120:123], v[168:171], v[16:19]
	v_mfma_f32_16x16x32_bf16 v[92:95], v[108:111], v[176:179], v[92:95]
	v_mfma_f32_16x16x32_bf16 v[4:7], v[120:123], v[176:179], v[4:7]
	v_mfma_f32_16x16x32_bf16 v[48:51], v[108:111], v[184:187], v[48:51]
	v_mfma_f32_16x16x32_bf16 v[40:43], v[120:123], v[184:187], v[40:43]
	v_mfma_f32_16x16x32_bf16 v[112:115], v[116:119], v[156:159], v[112:115]
	v_mfma_f32_16x16x32_bf16 v[20:23], v[124:127], v[156:159], v[20:23]
	v_mfma_f32_16x16x32_bf16 v[104:107], v[116:119], v[172:175], v[104:107]
	v_mfma_f32_16x16x32_bf16 v[16:19], v[124:127], v[172:175], v[16:19]
	v_mfma_f32_16x16x32_bf16 v[92:95], v[116:119], v[180:183], v[92:95]
	v_mfma_f32_16x16x32_bf16 v[4:7], v[124:127], v[180:183], v[4:7]
	v_mfma_f32_16x16x32_bf16 v[48:51], v[116:119], v[188:191], v[48:51]
	v_mfma_f32_16x16x32_bf16 v[40:43], v[124:127], v[188:191], v[40:43]
	s_setprio 0
	s_setprio 1
	v_mfma_f32_16x16x32_bf16 v[100:103], v[128:131], v[152:155], v[100:103]
	v_mfma_f32_16x16x32_bf16 v[12:15], v[136:139], v[152:155], v[12:15]
	v_mfma_f32_16x16x32_bf16 v[96:99], v[128:131], v[168:171], v[96:99]
	v_mfma_f32_16x16x32_bf16 v[8:11], v[136:139], v[168:171], v[8:11]
	v_mfma_f32_16x16x32_bf16 v[88:91], v[128:131], v[176:179], v[88:91]
	v_mfma_f32_16x16x32_bf16 v[0:3], v[136:139], v[176:179], v[0:3]
	v_mfma_f32_16x16x32_bf16 v[32:35], v[128:131], v[184:187], v[32:35]
	v_mfma_f32_16x16x32_bf16 v[24:27], v[136:139], v[184:187], v[24:27]
	v_mfma_f32_16x16x32_bf16 v[100:103], v[132:135], v[156:159], v[100:103]
	v_mfma_f32_16x16x32_bf16 v[12:15], v[140:143], v[156:159], v[12:15]
	v_mfma_f32_16x16x32_bf16 v[96:99], v[132:135], v[172:175], v[96:99]
	v_mfma_f32_16x16x32_bf16 v[8:11], v[140:143], v[172:175], v[8:11]
	v_mfma_f32_16x16x32_bf16 v[88:91], v[132:135], v[180:183], v[88:91]
	v_mfma_f32_16x16x32_bf16 v[0:3], v[140:143], v[180:183], v[0:3]
	v_mfma_f32_16x16x32_bf16 v[32:35], v[132:135], v[188:191], v[32:35]
	v_mfma_f32_16x16x32_bf16 v[24:27], v[140:143], v[188:191], v[24:27]
	s_setprio 0
	s_barrier
	s_add_i32 s87, 0, 0x18000
	s_add_i32 s96, 0, 0x1c000
	v_add_u32_e32 v124, s87, v205
	v_add_u32_e32 v140, s96, v205
	ds_read_b128 v[108:111], v124
	ds_read_b128 v[116:119], v124 offset:1024
	ds_read_b128 v[120:123], v124 offset:2048
	ds_read_b128 v[124:127], v124 offset:3072
	ds_read_b128 v[128:131], v140
	ds_read_b128 v[132:135], v140 offset:1024
	ds_read_b128 v[136:139], v140 offset:2048
	ds_read_b128 v[140:143], v140 offset:3072
	s_add_u32 s64, s64, 0x40000
	s_addc_u32 s65, s65, 0
	s_mov_b32 m0, s76
	v_lshl_add_u64 v[228:229], s[64:65], 0, v[192:193]
	ds_read_b128 v[152:155], v247 offset:32768
	ds_read_b128 v[156:159], v247 offset:33792
	ds_read_b128 v[168:171], v247 offset:34816
	ds_read_b128 v[172:175], v247 offset:35840
	ds_read_b128 v[176:179], v247 offset:36864
	ds_read_b128 v[180:183], v247 offset:37888
	ds_read_b128 v[184:187], v247 offset:38912
	ds_read_b128 v[188:191], v247 offset:39936
	global_load_lds_dwordx4 v[228:229], off
	v_lshl_add_u64 v[228:229], s[64:65], 0, v[198:199]
	s_mov_b32 m0, s77
	s_nop 0
	global_load_lds_dwordx4 v[228:229], off
	s_waitcnt vmcnt(8)
	s_waitcnt lgkmcnt(0)
	s_barrier
	s_setprio 1
	v_mfma_f32_16x16x32_bf16 v[52:55], v[108:111], v[152:155], v[52:55]
	v_mfma_f32_16x16x32_bf16 v[44:47], v[120:123], v[152:155], v[44:47]
	v_mfma_f32_16x16x32_bf16 v[164:167], v[108:111], v[168:171], v[164:167]
	v_mfma_f32_16x16x32_bf16 v[68:71], v[120:123], v[168:171], v[68:71]
	v_mfma_f32_16x16x32_bf16 v[160:163], v[108:111], v[176:179], v[160:163]
	v_mfma_f32_16x16x32_bf16 v[60:63], v[120:123], v[176:179], v[60:63]
	v_mfma_f32_16x16x32_bf16 v[84:87], v[108:111], v[184:187], v[84:87]
	v_mfma_f32_16x16x32_bf16 v[80:83], v[120:123], v[184:187], v[80:83]
	v_mfma_f32_16x16x32_bf16 v[52:55], v[116:119], v[156:159], v[52:55]
	v_mfma_f32_16x16x32_bf16 v[44:47], v[124:127], v[156:159], v[44:47]
	v_mfma_f32_16x16x32_bf16 v[164:167], v[116:119], v[172:175], v[164:167]
	v_mfma_f32_16x16x32_bf16 v[68:71], v[124:127], v[172:175], v[68:71]
	v_mfma_f32_16x16x32_bf16 v[160:163], v[116:119], v[180:183], v[160:163]
	v_mfma_f32_16x16x32_bf16 v[60:63], v[124:127], v[180:183], v[60:63]
	v_mfma_f32_16x16x32_bf16 v[84:87], v[116:119], v[188:191], v[84:87]
	v_mfma_f32_16x16x32_bf16 v[80:83], v[124:127], v[188:191], v[80:83]
	s_setprio 0
	s_setprio 1
	v_mfma_f32_16x16x32_bf16 v[144:147], v[128:131], v[168:171], v[144:147]
	v_mfma_f32_16x16x32_bf16 v[36:39], v[128:131], v[152:155], v[36:39]
	v_mfma_f32_16x16x32_bf16 v[28:31], v[136:139], v[152:155], v[28:31]
	v_mfma_f32_16x16x32_bf16 v[152:155], v[132:135], v[172:175], v[144:147]
	v_mfma_f32_16x16x32_bf16 v[64:67], v[136:139], v[168:171], v[64:67]
	v_mfma_f32_16x16x32_bf16 v[144:147], v[128:131], v[176:179], v[148:151]
	v_mfma_f32_16x16x32_bf16 v[56:59], v[136:139], v[176:179], v[56:59]
	v_mfma_f32_16x16x32_bf16 v[76:79], v[128:131], v[184:187], v[76:79]
	v_mfma_f32_16x16x32_bf16 v[72:75], v[136:139], v[184:187], v[72:75]
	v_mfma_f32_16x16x32_bf16 v[36:39], v[132:135], v[156:159], v[36:39]
	v_mfma_f32_16x16x32_bf16 v[28:31], v[140:143], v[156:159], v[28:31]
	v_mfma_f32_16x16x32_bf16 v[64:67], v[140:143], v[172:175], v[64:67]
	v_mfma_f32_16x16x32_bf16 v[156:159], v[132:135], v[180:183], v[144:147]
	v_mfma_f32_16x16x32_bf16 v[56:59], v[140:143], v[180:183], v[56:59]
	v_mfma_f32_16x16x32_bf16 v[76:79], v[132:135], v[188:191], v[76:79]
	v_mfma_f32_16x16x32_bf16 v[72:75], v[140:143], v[188:191], v[72:75]
	s_setprio 0
	s_barrier
	s_add_i32 s64, s87, s73
	v_lshl_add_u64 v[220:221], v[220:221], 0, s[20:21]
	s_mov_b32 m0, s64
	ds_read_b128 v[144:147], v247 offset:49152
	ds_read_b128 v[148:151], v247 offset:50176
	ds_read_b128 v[168:171], v247 offset:51200
	ds_read_b128 v[172:175], v247 offset:52224
	ds_read_b128 v[176:179], v247 offset:53248
	ds_read_b128 v[180:183], v247 offset:54272
	ds_read_b128 v[184:187], v247 offset:55296
	ds_read_b128 v[188:191], v247 offset:56320
	global_load_lds_dwordx4 v[220:221], off
	s_add_i32 m0, s64, 0x2000
	s_add_u32 s62, s62, 0x40080
	v_lshl_add_u64 v[220:221], v[222:223], 0, s[20:21]
	s_addc_u32 s63, s63, 0
	s_add_i32 s64, s96, s73
	global_load_lds_dwordx4 v[220:221], off
	v_lshl_add_u64 v[220:221], s[62:63], 0, v[194:195]
	s_mov_b32 m0, s64
	s_nop 0
	global_load_lds_dwordx4 v[220:221], off
	v_lshl_add_u64 v[220:221], s[62:63], 0, v[200:201]
	s_add_i32 m0, s64, 0x2000
	s_nop 0
	global_load_lds_dwordx4 v[220:221], off
	v_lshl_add_u64 v[220:221], v[224:225], 0, s[20:21]
	s_mov_b32 m0, s80
	s_nop 0
	global_load_lds_dwordx4 v[220:221], off
	v_lshl_add_u64 v[220:221], v[226:227], 0, s[20:21]
	s_mov_b32 m0, s81
	s_nop 0
	global_load_lds_dwordx4 v[220:221], off
	s_waitcnt vmcnt(8)
	s_waitcnt lgkmcnt(0)
	s_barrier
	s_setprio 1
	v_mfma_f32_16x16x32_bf16 v[112:115], v[108:111], v[144:147], v[112:115]
	v_mfma_f32_16x16x32_bf16 v[20:23], v[120:123], v[144:147], v[20:23]
	v_mfma_f32_16x16x32_bf16 v[104:107], v[108:111], v[168:171], v[104:107]
	v_mfma_f32_16x16x32_bf16 v[16:19], v[120:123], v[168:171], v[16:19]
	v_mfma_f32_16x16x32_bf16 v[92:95], v[108:111], v[176:179], v[92:95]
	v_mfma_f32_16x16x32_bf16 v[4:7], v[120:123], v[176:179], v[4:7]
	v_mfma_f32_16x16x32_bf16 v[48:51], v[108:111], v[184:187], v[48:51]
	v_mfma_f32_16x16x32_bf16 v[40:43], v[120:123], v[184:187], v[40:43]
	v_mfma_f32_16x16x32_bf16 v[112:115], v[116:119], v[148:151], v[112:115]
	v_mfma_f32_16x16x32_bf16 v[20:23], v[124:127], v[148:151], v[20:23]
	v_mfma_f32_16x16x32_bf16 v[104:107], v[116:119], v[172:175], v[104:107]
	v_mfma_f32_16x16x32_bf16 v[16:19], v[124:127], v[172:175], v[16:19]
	v_mfma_f32_16x16x32_bf16 v[92:95], v[116:119], v[180:183], v[92:95]
	v_mfma_f32_16x16x32_bf16 v[4:7], v[124:127], v[180:183], v[4:7]
	v_mfma_f32_16x16x32_bf16 v[48:51], v[116:119], v[188:191], v[48:51]
	v_mfma_f32_16x16x32_bf16 v[40:43], v[124:127], v[188:191], v[40:43]
	s_setprio 0
	s_setprio 1
	v_mfma_f32_16x16x32_bf16 v[100:103], v[128:131], v[144:147], v[100:103]
	v_mfma_f32_16x16x32_bf16 v[12:15], v[136:139], v[144:147], v[12:15]
	v_mfma_f32_16x16x32_bf16 v[96:99], v[128:131], v[168:171], v[96:99]
	v_mfma_f32_16x16x32_bf16 v[8:11], v[136:139], v[168:171], v[8:11]
	v_mfma_f32_16x16x32_bf16 v[88:91], v[128:131], v[176:179], v[88:91]
	v_mfma_f32_16x16x32_bf16 v[0:3], v[136:139], v[176:179], v[0:3]
	v_mfma_f32_16x16x32_bf16 v[32:35], v[128:131], v[184:187], v[32:35]
	v_mfma_f32_16x16x32_bf16 v[24:27], v[136:139], v[184:187], v[24:27]
	v_mfma_f32_16x16x32_bf16 v[100:103], v[132:135], v[148:151], v[100:103]
	v_mfma_f32_16x16x32_bf16 v[12:15], v[140:143], v[148:151], v[12:15]
	v_mfma_f32_16x16x32_bf16 v[96:99], v[132:135], v[172:175], v[96:99]
	v_mfma_f32_16x16x32_bf16 v[8:11], v[140:143], v[172:175], v[8:11]
	v_mfma_f32_16x16x32_bf16 v[88:91], v[132:135], v[180:183], v[88:91]
	v_mfma_f32_16x16x32_bf16 v[0:3], v[140:143], v[180:183], v[0:3]
	v_mfma_f32_16x16x32_bf16 v[32:35], v[132:135], v[188:191], v[32:35]
	v_mfma_f32_16x16x32_bf16 v[24:27], v[140:143], v[188:191], v[24:27]
	s_setprio 0
	s_barrier
	s_add_i32 s86, s86, 2
	s_add_u32 s8, s8, 0x100
	s_addc_u32 s9, s9, 0
	s_add_u32 s59, s59, 0x100
	s_addc_u32 s61, s61, 0
	s_cmp_gt_u32 s86, 13
	s_cbranch_scc0 .LBB0_577
	s_and_b64 vcc, exec, s[26:27]
	s_cbranch_vccz .LBB0_580
	s_barrier

.Lp6_nopf:
	s_waitcnt lgkmcnt(0)
	s_barrier
	s_setprio 1
	v_mfma_f32_16x16x32_bf16 v[124:127], v[128:131], v[160:163], v[124:127]
	v_mfma_f32_16x16x32_bf16 v[120:123], v[136:139], v[160:163], v[120:123]
	v_mfma_f32_16x16x32_bf16 v[112:115], v[128:131], v[184:187], v[112:115]
	v_mfma_f32_16x16x32_bf16 v[104:107], v[136:139], v[184:187], v[104:107]
	v_mfma_f32_16x16x32_bf16 v[96:99], v[128:131], v[198:201], v[96:99]
	v_mfma_f32_16x16x32_bf16 v[88:91], v[136:139], v[198:201], v[88:91]
	v_mfma_f32_16x16x32_bf16 v[80:83], v[128:131], v[206:209], v[80:83]
	v_mfma_f32_16x16x32_bf16 v[72:75], v[136:139], v[206:209], v[72:75]
	v_mfma_f32_16x16x32_bf16 v[124:127], v[132:135], v[180:183], v[124:127]
	v_mfma_f32_16x16x32_bf16 v[120:123], v[140:143], v[180:183], v[120:123]
	v_mfma_f32_16x16x32_bf16 v[112:115], v[132:135], v[188:191], v[112:115]
	v_mfma_f32_16x16x32_bf16 v[104:107], v[140:143], v[188:191], v[104:107]
	v_mfma_f32_16x16x32_bf16 v[96:99], v[132:135], v[202:205], v[96:99]
	v_mfma_f32_16x16x32_bf16 v[88:91], v[140:143], v[202:205], v[88:91]
	v_mfma_f32_16x16x32_bf16 v[80:83], v[132:135], v[210:213], v[80:83]
	v_mfma_f32_16x16x32_bf16 v[72:75], v[140:143], v[210:213], v[72:75]
	s_setprio 0
	s_setprio 1
	v_mfma_f32_16x16x32_bf16 v[116:119], v[144:147], v[160:163], v[116:119]
	v_mfma_f32_16x16x32_bf16 v[108:111], v[152:155], v[160:163], v[108:111]
	v_mfma_f32_16x16x32_bf16 v[100:103], v[144:147], v[184:187], v[100:103]
	v_mfma_f32_16x16x32_bf16 v[92:95], v[152:155], v[184:187], v[92:95]
	v_mfma_f32_16x16x32_bf16 v[84:87], v[144:147], v[198:201], v[84:87]
	v_mfma_f32_16x16x32_bf16 v[76:79], v[152:155], v[198:201], v[76:79]
	v_mfma_f32_16x16x32_bf16 v[68:71], v[144:147], v[206:209], v[68:71]
	v_mfma_f32_16x16x32_bf16 v[64:67], v[152:155], v[206:209], v[64:67]
	v_mfma_f32_16x16x32_bf16 v[116:119], v[148:151], v[180:183], v[116:119]
	v_mfma_f32_16x16x32_bf16 v[108:111], v[156:159], v[180:183], v[108:111]
	v_mfma_f32_16x16x32_bf16 v[100:103], v[148:151], v[188:191], v[100:103]
	v_mfma_f32_16x16x32_bf16 v[92:95], v[156:159], v[188:191], v[92:95]
	v_mfma_f32_16x16x32_bf16 v[84:87], v[148:151], v[202:205], v[84:87]
	v_mfma_f32_16x16x32_bf16 v[76:79], v[156:159], v[202:205], v[76:79]
	v_mfma_f32_16x16x32_bf16 v[68:71], v[148:151], v[210:213], v[68:71]
	v_mfma_f32_16x16x32_bf16 v[64:67], v[156:159], v[210:213], v[64:67]
	s_setprio 0
	s_barrier
	s_add_i32 s18, s39, s28
	v_lshl_add_u64 v[214:215], s[22:23], 0, v[166:167]
	s_mov_b32 m0, s18
	ds_read_b128 v[160:163], v197 offset:16384
	ds_read_b128 v[180:183], v197 offset:17408
	ds_read_b128 v[184:187], v197 offset:18432
	ds_read_b128 v[188:191], v197 offset:19456
	ds_read_b128 v[198:201], v197 offset:20480
	ds_read_b128 v[202:205], v197 offset:21504
	ds_read_b128 v[206:209], v197 offset:22528
	ds_read_b128 v[210:213], v197 offset:23552
	global_load_lds_dwordx4 v[214:215], off
	s_add_i32 m0, s18, 0x2000
	s_add_u32 s18, s22, 0xb0000
	v_lshl_add_u64 v[216:217], s[22:23], 0, v[170:171]
	s_addc_u32 s19, s23, 0
	s_add_i32 s48, s40, s28
	global_load_lds_dwordx4 v[216:217], off
	v_lshl_add_u64 v[218:219], s[18:19], 0, v[166:167]
	s_mov_b32 m0, s48
	v_lshl_add_u64 v[220:221], s[24:25], 0, v[168:169]
	global_load_lds_dwordx4 v[218:219], off
	v_lshl_add_u64 v[218:219], s[18:19], 0, v[170:171]
	s_add_i32 m0, s48, 0x2000
	s_nop 0
	global_load_lds_dwordx4 v[218:219], off
	v_lshl_add_u64 v[218:219], s[24:25], 0, v[164:165]
	s_mov_b32 m0, s29
	s_nop 0
	global_load_lds_dwordx4 v[218:219], off
	s_mov_b32 m0, s33
	s_nop 0
	global_load_lds_dwordx4 v[220:221], off
	s_waitcnt vmcnt(8)
	s_waitcnt lgkmcnt(0)
	s_barrier
	s_setprio 1
	v_mfma_f32_16x16x32_bf16 v[60:63], v[128:131], v[160:163], v[60:63]
	v_mfma_f32_16x16x32_bf16 v[56:59], v[136:139], v[160:163], v[56:59]
	v_mfma_f32_16x16x32_bf16 v[48:51], v[128:131], v[184:187], v[48:51]
	v_mfma_f32_16x16x32_bf16 v[40:43], v[136:139], v[184:187], v[40:43]
	v_mfma_f32_16x16x32_bf16 v[32:35], v[128:131], v[198:201], v[32:35]
	v_mfma_f32_16x16x32_bf16 v[24:27], v[136:139], v[198:201], v[24:27]
	v_mfma_f32_16x16x32_bf16 v[16:19], v[128:131], v[206:209], v[16:19]
	v_mfma_f32_16x16x32_bf16 v[8:11], v[136:139], v[206:209], v[8:11]
	v_mfma_f32_16x16x32_bf16 v[60:63], v[132:135], v[180:183], v[60:63]
	v_mfma_f32_16x16x32_bf16 v[56:59], v[140:143], v[180:183], v[56:59]
	v_mfma_f32_16x16x32_bf16 v[48:51], v[132:135], v[188:191], v[48:51]
	v_mfma_f32_16x16x32_bf16 v[40:43], v[140:143], v[188:191], v[40:43]
	v_mfma_f32_16x16x32_bf16 v[32:35], v[132:135], v[202:205], v[32:35]
	v_mfma_f32_16x16x32_bf16 v[24:27], v[140:143], v[202:205], v[24:27]
	v_mfma_f32_16x16x32_bf16 v[16:19], v[132:135], v[210:213], v[16:19]
	v_mfma_f32_16x16x32_bf16 v[8:11], v[140:143], v[210:213], v[8:11]
	s_setprio 0
	s_setprio 1
	v_mfma_f32_16x16x32_bf16 v[52:55], v[144:147], v[160:163], v[52:55]
	v_mfma_f32_16x16x32_bf16 v[44:47], v[152:155], v[160:163], v[44:47]
	v_mfma_f32_16x16x32_bf16 v[36:39], v[144:147], v[184:187], v[36:39]
	v_mfma_f32_16x16x32_bf16 v[28:31], v[152:155], v[184:187], v[28:31]
	v_mfma_f32_16x16x32_bf16 v[20:23], v[144:147], v[198:201], v[20:23]
	v_mfma_f32_16x16x32_bf16 v[12:15], v[152:155], v[198:201], v[12:15]
	v_mfma_f32_16x16x32_bf16 v[4:7], v[144:147], v[206:209], v[4:7]
	v_mfma_f32_16x16x32_bf16 v[0:3], v[152:155], v[206:209], v[0:3]
	v_mfma_f32_16x16x32_bf16 v[52:55], v[148:151], v[180:183], v[52:55]
	v_mfma_f32_16x16x32_bf16 v[44:47], v[156:159], v[180:183], v[44:47]
	v_mfma_f32_16x16x32_bf16 v[36:39], v[148:151], v[188:191], v[36:39]
	v_mfma_f32_16x16x32_bf16 v[28:31], v[156:159], v[188:191], v[28:31]
	v_mfma_f32_16x16x32_bf16 v[20:23], v[148:151], v[202:205], v[20:23]
	v_mfma_f32_16x16x32_bf16 v[12:15], v[156:159], v[202:205], v[12:15]
	v_mfma_f32_16x16x32_bf16 v[4:7], v[148:151], v[210:213], v[4:7]
	v_mfma_f32_16x16x32_bf16 v[0:3], v[156:159], v[210:213], v[0:3]
	s_setprio 0
	s_barrier
	s_add_i32 s48, 0, 0x18000
	s_add_i32 s49, 0, 0x1c000
	v_add_u32_e32 v140, s48, v193
	v_add_u32_e32 v156, s49, v193
	ds_read_b128 v[128:131], v140
	ds_read_b128 v[132:135], v140 offset:1024
	ds_read_b128 v[136:139], v140 offset:2048
	ds_read_b128 v[140:143], v140 offset:3072
	ds_read_b128 v[144:147], v156
	ds_read_b128 v[148:151], v156 offset:1024
	ds_read_b128 v[152:155], v156 offset:2048
	ds_read_b128 v[156:159], v156 offset:3072
	s_add_u32 s18, s24, 0xb0000
	s_addc_u32 s19, s25, 0
	s_mov_b32 m0, s34
	v_lshl_add_u64 v[222:223], s[18:19], 0, v[164:165]
	ds_read_b128 v[160:163], v197 offset:32768
	ds_read_b128 v[180:183], v197 offset:33792
	ds_read_b128 v[184:187], v197 offset:34816
	ds_read_b128 v[188:191], v197 offset:35840
	ds_read_b128 v[198:201], v197 offset:36864
	ds_read_b128 v[202:205], v197 offset:37888
	ds_read_b128 v[206:209], v197 offset:38912
	ds_read_b128 v[210:213], v197 offset:39936
	global_load_lds_dwordx4 v[222:223], off
	v_lshl_add_u64 v[222:223], s[18:19], 0, v[168:169]
	s_mov_b32 m0, s35
	s_nop 0
	global_load_lds_dwordx4 v[222:223], off
	s_waitcnt vmcnt(8)
	s_waitcnt lgkmcnt(0)
	s_barrier
	s_setprio 1
	v_mfma_f32_16x16x32_bf16 v[124:127], v[128:131], v[160:163], v[124:127]
	v_mfma_f32_16x16x32_bf16 v[120:123], v[136:139], v[160:163], v[120:123]
	v_mfma_f32_16x16x32_bf16 v[112:115], v[128:131], v[184:187], v[112:115]
	v_mfma_f32_16x16x32_bf16 v[104:107], v[136:139], v[184:187], v[104:107]
	v_mfma_f32_16x16x32_bf16 v[96:99], v[128:131], v[198:201], v[96:99]
	v_mfma_f32_16x16x32_bf16 v[88:91], v[136:139], v[198:201], v[88:91]
	v_mfma_f32_16x16x32_bf16 v[80:83], v[128:131], v[206:209], v[80:83]
	v_mfma_f32_16x16x32_bf16 v[72:75], v[136:139], v[206:209], v[72:75]
	v_mfma_f32_16x16x32_bf16 v[124:127], v[132:135], v[180:183], v[124:127]
	v_mfma_f32_16x16x32_bf16 v[120:123], v[140:143], v[180:183], v[120:123]
	v_mfma_f32_16x16x32_bf16 v[112:115], v[132:135], v[188:191], v[112:115]
	v_mfma_f32_16x16x32_bf16 v[104:107], v[140:143], v[188:191], v[104:107]
	v_mfma_f32_16x16x32_bf16 v[96:99], v[132:135], v[202:205], v[96:99]
	v_mfma_f32_16x16x32_bf16 v[88:91], v[140:143], v[202:205], v[88:91]
	v_mfma_f32_16x16x32_bf16 v[80:83], v[132:135], v[210:213], v[80:83]
	v_mfma_f32_16x16x32_bf16 v[72:75], v[140:143], v[210:213], v[72:75]
	s_setprio 0
	s_setprio 1
	v_mfma_f32_16x16x32_bf16 v[116:119], v[144:147], v[160:163], v[116:119]
	v_mfma_f32_16x16x32_bf16 v[108:111], v[152:155], v[160:163], v[108:111]
	v_mfma_f32_16x16x32_bf16 v[100:103], v[144:147], v[184:187], v[100:103]
	v_mfma_f32_16x16x32_bf16 v[92:95], v[152:155], v[184:187], v[92:95]
	v_mfma_f32_16x16x32_bf16 v[84:87], v[144:147], v[198:201], v[84:87]
	v_mfma_f32_16x16x32_bf16 v[76:79], v[152:155], v[198:201], v[76:79]
	v_mfma_f32_16x16x32_bf16 v[68:71], v[144:147], v[206:209], v[68:71]
	v_mfma_f32_16x16x32_bf16 v[64:67], v[152:155], v[206:209], v[64:67]
	v_mfma_f32_16x16x32_bf16 v[116:119], v[148:151], v[180:183], v[116:119]
	v_mfma_f32_16x16x32_bf16 v[108:111], v[156:159], v[180:183], v[108:111]
	v_mfma_f32_16x16x32_bf16 v[100:103], v[148:151], v[188:191], v[100:103]
	v_mfma_f32_16x16x32_bf16 v[92:95], v[156:159], v[188:191], v[92:95]
	v_mfma_f32_16x16x32_bf16 v[84:87], v[148:151], v[202:205], v[84:87]
	v_mfma_f32_16x16x32_bf16 v[76:79], v[156:159], v[202:205], v[76:79]
	v_mfma_f32_16x16x32_bf16 v[68:71], v[148:151], v[210:213], v[68:71]
	v_mfma_f32_16x16x32_bf16 v[64:67], v[156:159], v[210:213], v[64:67]
	s_setprio 0
	s_barrier
	s_add_i32 s18, s48, s28
	v_lshl_add_u64 v[214:215], v[214:215], 0, s[10:11]
	s_mov_b32 m0, s18
	ds_read_b128 v[160:163], v197 offset:49152
	ds_read_b128 v[180:183], v197 offset:50176
	ds_read_b128 v[184:187], v197 offset:51200
	ds_read_b128 v[188:191], v197 offset:52224
	ds_read_b128 v[198:201], v197 offset:53248
	ds_read_b128 v[202:205], v197 offset:54272
	ds_read_b128 v[206:209], v197 offset:55296
	ds_read_b128 v[210:213], v197 offset:56320
	global_load_lds_dwordx4 v[214:215], off
	s_add_i32 m0, s18, 0x2000
	s_add_u32 s18, s22, 0xb0080
	v_lshl_add_u64 v[214:215], v[216:217], 0, s[10:11]
	s_addc_u32 s19, s23, 0
	s_add_i32 s22, s49, s28
	global_load_lds_dwordx4 v[214:215], off
	v_lshl_add_u64 v[214:215], s[18:19], 0, v[166:167]
	s_mov_b32 m0, s22
	s_nop 0
	global_load_lds_dwordx4 v[214:215], off
	v_lshl_add_u64 v[214:215], s[18:19], 0, v[170:171]
	s_add_i32 m0, s22, 0x2000
	s_nop 0
	global_load_lds_dwordx4 v[214:215], off
	v_lshl_add_u64 v[214:215], v[218:219], 0, s[10:11]
	s_mov_b32 m0, s37
	s_nop 0
	global_load_lds_dwordx4 v[214:215], off
	v_lshl_add_u64 v[214:215], v[220:221], 0, s[10:11]
	s_mov_b32 m0, s38
	s_nop 0
	global_load_lds_dwordx4 v[214:215], off
	s_waitcnt vmcnt(8)
	s_waitcnt lgkmcnt(0)
	s_barrier
	s_setprio 1
	v_mfma_f32_16x16x32_bf16 v[60:63], v[128:131], v[160:163], v[60:63]
	v_mfma_f32_16x16x32_bf16 v[56:59], v[136:139], v[160:163], v[56:59]
	v_mfma_f32_16x16x32_bf16 v[48:51], v[128:131], v[184:187], v[48:51]
	v_mfma_f32_16x16x32_bf16 v[40:43], v[136:139], v[184:187], v[40:43]
	v_mfma_f32_16x16x32_bf16 v[32:35], v[128:131], v[198:201], v[32:35]
	v_mfma_f32_16x16x32_bf16 v[24:27], v[136:139], v[198:201], v[24:27]
	v_mfma_f32_16x16x32_bf16 v[16:19], v[128:131], v[206:209], v[16:19]
	v_mfma_f32_16x16x32_bf16 v[8:11], v[136:139], v[206:209], v[8:11]
	v_mfma_f32_16x16x32_bf16 v[60:63], v[132:135], v[180:183], v[60:63]
	v_mfma_f32_16x16x32_bf16 v[56:59], v[140:143], v[180:183], v[56:59]
	v_mfma_f32_16x16x32_bf16 v[48:51], v[132:135], v[188:191], v[48:51]
	v_mfma_f32_16x16x32_bf16 v[40:43], v[140:143], v[188:191], v[40:43]
	v_mfma_f32_16x16x32_bf16 v[32:35], v[132:135], v[202:205], v[32:35]
	v_mfma_f32_16x16x32_bf16 v[24:27], v[140:143], v[202:205], v[24:27]
	v_mfma_f32_16x16x32_bf16 v[16:19], v[132:135], v[210:213], v[16:19]
	v_mfma_f32_16x16x32_bf16 v[8:11], v[140:143], v[210:213], v[8:11]
	s_setprio 0
	s_setprio 1
	v_mfma_f32_16x16x32_bf16 v[52:55], v[144:147], v[160:163], v[52:55]
	v_mfma_f32_16x16x32_bf16 v[44:47], v[152:155], v[160:163], v[44:47]
	v_mfma_f32_16x16x32_bf16 v[36:39], v[144:147], v[184:187], v[36:39]
	v_mfma_f32_16x16x32_bf16 v[28:31], v[152:155], v[184:187], v[28:31]
	v_mfma_f32_16x16x32_bf16 v[20:23], v[144:147], v[198:201], v[20:23]
	v_mfma_f32_16x16x32_bf16 v[12:15], v[152:155], v[198:201], v[12:15]
	v_mfma_f32_16x16x32_bf16 v[4:7], v[144:147], v[206:209], v[4:7]
	v_mfma_f32_16x16x32_bf16 v[0:3], v[152:155], v[206:209], v[0:3]
	v_mfma_f32_16x16x32_bf16 v[52:55], v[148:151], v[180:183], v[52:55]
	v_mfma_f32_16x16x32_bf16 v[44:47], v[156:159], v[180:183], v[44:47]
	v_mfma_f32_16x16x32_bf16 v[36:39], v[148:151], v[188:191], v[36:39]
	v_mfma_f32_16x16x32_bf16 v[28:31], v[156:159], v[188:191], v[28:31]
	v_mfma_f32_16x16x32_bf16 v[20:23], v[148:151], v[202:205], v[20:23]
	v_mfma_f32_16x16x32_bf16 v[12:15], v[156:159], v[202:205], v[12:15]
	v_mfma_f32_16x16x32_bf16 v[4:7], v[148:151], v[210:213], v[4:7]
	v_mfma_f32_16x16x32_bf16 v[0:3], v[156:159], v[210:213], v[0:3]
	s_setprio 0
	s_barrier
	s_add_i32 s47, s47, 2
	s_add_u32 s45, s45, 0x100
	s_addc_u32 s46, s46, 0
	s_cmp_gt_u32 s47, 41
	s_mov_b64 s[18:19], s[20:21]
	s_cbranch_scc0 .LBB0_687
	s_and_b64 vcc, exec, s[12:13]
	s_cbranch_vccz .LBB0_690
	s_barrier
